# v105 + fox stage loop: c value loaded straight into its carried register, chunk prefix added at the LDS store block (no vmcnt(0) right after the prefetch issue in waves 0/1)
# baseline (speedup 1.0000x reference)
; #define FOX_LOAD(T) do { const bf16* kg = Kb + (tokb + 128 * (T) + kvs) * 1024 + col + 8 * ch; const bf16* vg = Vb + (tokb + 128 * (T) + vkey0) * 1024 + col + vcol0; \
;         kreg[0] = *(const u32x4*)(kg); kreg[1] = *(const u32x4*)(kg + 64 * 1024); vreg[0] = *(const u32x4*)(vg); vreg[1] = *(const u32x4*)(vg + 16 * 1024); \
;         if (tid < 128) creg = clp[128 * (T) + tid] + pre[(T)]; } while (0)
; __device__ __forceinline__ void fox_phase(LAS unsigned char* lds, int L) {
;     ...
;         for (int it = 0; it < NT; ++it) {
;             const int T = NT - 1 - it;
;             if (it + 1 < NT) FOX_LOAD(T - 1);
.LBB0_227:
	s_add_i32 s43, s3, 1
	s_cmp_lt_u32 s43, s38
	s_cselect_b64 s[22:23], -1, 0
	s_cmp_ge_u32 s43, s38
	s_cbranch_scc1 .LBB0_231
	s_add_u32 s44, s72, 0xe400000
	s_addc_u32 s45, s73, 0
	v_lshl_add_u64 v[6:7], v[160:161], 0, s[44:45]
	global_load_dwordx4 v[116:119], v[6:7], off offset:1024
	s_add_u32 s44, s72, 0xe420000
	s_addc_u32 s45, s73, 0
	v_lshl_add_u64 v[0:1], v[160:161], 0, s[44:45]
	global_load_dwordx4 v[120:123], v[0:1], off offset:1024
	s_add_u32 s44, s72, 0x12400000
	s_addc_u32 s45, s73, 0
	v_lshl_add_u64 v[6:7], v[158:159], 0, s[44:45]
	global_load_dwordx4 v[124:127], v[6:7], off offset:1024
	s_add_u32 s44, s72, 0x12408000
	s_addc_u32 s45, s73, 0
	v_lshl_add_u64 v[0:1], v[158:159], 0, s[44:45]
	global_load_dwordx4 v[128:131], v[0:1], off offset:1024
	s_and_saveexec_b64 s[24:25], s[4:5]
	s_cbranch_execz .LBB0_230
	v_add_u32_e32 v0, s36, v183
	v_ashrrev_i32_e32 v1, 31, v0
	v_lshl_add_u64 v[0:1], v[0:1], 2, s[20:21]
	global_load_dword v179, v[0:1], off

; __device__ __forceinline__ void fox_phase(LAS unsigned char* lds, int L) {
;     ...
;             if (it + 1 < NT) FOX_STORE((it + 1) & 1);
.LBB0_248:
	s_bitcmp1_b32 s43, 0
	s_cselect_b32 s3, 0x9000, 0
	v_add_u32_e32 v0, s3, v136
	s_waitcnt vmcnt(0)
	ds_write_b128 v0, v[116:119]
	ds_write_b128 v0, v[120:123] offset:9216
	v_add_u32_e32 v0, s3, v141
	ds_write_b128 v0, v[124:127] offset:18432
	ds_write_b128 v0, v[128:131] offset:19456
	s_and_saveexec_b64 s[22:23], s[4:5]
	s_cbranch_execz .LBB0_250
	v_mov_b32_e32 v1, s40
	ds_read_b32 v1, v1
	s_waitcnt lgkmcnt(0)
	v_add_f32_e32 v179, v179, v1
	v_mul_f32_e32 v0, 0xbfb8aa3b, v179
	v_bfe_u32 v1, v0, 16, 1
	v_add3_u32 v0, v0, v1, s89
	v_and_b32_e32 v1, 0xffff0000, v0
	v_fma_f32 v1, v179, s98, -v1
	v_bfe_u32 v3, v1, 16, 1
	v_add3_u32 v3, v1, v3, s89
	v_and_b32_e32 v3, 0xffff0000, v3
	v_sub_f32_e32 v1, v1, v3
	v_bfe_u32 v4, v1, 16, 1
	v_add3_u32 v1, v1, v4, s89
	v_lshrrev_b32_e32 v1, 16, v1
	v_or_b32_sdwa v0, v3, v0 dst_sel:DWORD dst_unused:UNUSED_PAD src0_sel:DWORD src1_sel:WORD_1
	v_mov_b32_e32 v3, v2
	v_add_u32_e32 v4, s3, v167
	ds_write_b128 v4, v[0:3] offset:34816
